# dilated attention per-wave-unit T5-bias slice staging: 4 serialized loads batched with one wait (3 pattern copies)
# baseline (speedup 1.0000x reference)
; template <int P_>
; __device__ __forceinline__ void dil_wave_unit(LAS unsigned char* wl, const bf16_t* DIL, bf16_t* Y, bf16_t* ST, float* LSE, const float* BT, int b, int h, int r, int nb) {
;     ...
;     for (int i = lane; i < 257; i += 64) { int j = i - 64; j = j < 0 ? 0 : (j > 128 ? 128 : j); bt[i] = BT[(P_ * 8 + h) * 129 + j]; }
;     const int btb = 128 * 4;
.LBB0_434:
	v_mov_b32_e32 v2, v221
	global_load_dword v6, v1, s[94:95]
	v_and_b32_e32 v209, 63, v2
	v_add_u32_e32 v7, s34, v209
	v_add_u32_e32 v0, 64, v7
	v_lshl_add_u64 v[4:5], v[0:1], 2, s[16:17]
	global_load_dword v240, v[4:5], off
	v_lshl_add_u32 v3, v209, 2, s10
	v_add_u32_e32 v0, 0x80, v7
	v_lshl_add_u64 v[4:5], v[0:1], 2, s[16:17]
	global_load_dword v241, v[4:5], off
	global_load_dword v0, v1, s[94:95] offset:512
	v_sub_u32_e32 v4, 64, v209
	v_lshrrev_b32_e32 v4, 6, v4
	v_cmp_ne_u32_e32 vcc, 0, v4
	s_waitcnt vmcnt(0)
	ds_write2st64_b32 v3, v6, v240 offset0:48 offset1:49
	ds_write_b32 v3, v241 offset:12800
	s_mov_b64 s[6:7], exec
	s_mov_b64 s[38:39], -1
	s_and_b64 s[38:39], s[6:7], s[38:39]
	s_mov_b64 exec, s[38:39]
	s_cbranch_execz .LBB0_436
	s_waitcnt vmcnt(0)
	ds_write_b32 v3, v0 offset:13056

; template <int P_>
; __device__ __forceinline__ void dil_wave_unit(LAS unsigned char* wl, const bf16_t* DIL, bf16_t* Y, bf16_t* ST, float* LSE, const float* BT, int b, int h, int r, int nb) {
;     ...
;     for (int i = lane; i < 257; i += 64) { int j = i - 64; j = j < 0 ? 0 : (j > 128 ? 128 : j); bt[i] = BT[(P_ * 8 + h) * 129 + j]; }
;     const int btb = 128 * 4;
.LBB0_448:
	v_mov_b32_e32 v2, v221
	global_load_dword v3, v1, s[6:7]
	v_and_b32_e32 v209, 63, v2
	v_lshlrev_b32_e32 v4, 2, v209
	v_or_b32_e32 v5, 0x100, v4
	global_load_dword v5, v5, s[94:95] offset:3872
	v_add_u32_e32 v0, s10, v4
	v_or_b32_e32 v240, 0x200, v4
	global_load_dword v240, v240, s[94:95] offset:3872
	global_load_dword v241, v1, s[88:89]
	v_sub_u32_e32 v4, 64, v209
	v_lshrrev_b32_e32 v4, 6, v4
	v_cmp_ne_u32_e32 vcc, 0, v4
	s_waitcnt vmcnt(0)
	ds_write2st64_b32 v0, v3, v5 offset0:48 offset1:49
	ds_write_b32 v0, v240 offset:12800
	v_mov_b32_e32 v3, v241
	s_mov_b64 s[34:35], exec
	s_mov_b64 s[40:41], -1
	s_and_b64 s[40:41], s[34:35], s[40:41]
	s_mov_b64 exec, s[40:41]
	s_cbranch_execz .LBB0_450
	s_waitcnt vmcnt(0)
	ds_write_b32 v0, v3 offset:13056

; template <int P_>
; __device__ __forceinline__ void dil_wave_unit(LAS unsigned char* wl, const bf16_t* DIL, bf16_t* Y, bf16_t* ST, float* LSE, const float* BT, int b, int h, int r, int nb) {
;     ...
;     for (int i = lane; i < 257; i += 64) { int j = i - 64; j = j < 0 ? 0 : (j > 128 ? 128 : j); bt[i] = BT[(P_ * 8 + h) * 129 + j]; }
;     const int btb = 128 * 4;
.LBB0_463:
	s_nop 0
	v_mov_b32_e32 v2, v221
	global_load_dword v6, v1, s[88:89]
	v_and_b32_e32 v209, 63, v2
	v_lshlrev_b32_e32 v7, 2, v209
	v_or_b32_e32 v0, 0x100, v7
	v_lshl_add_u64 v[4:5], s[94:95], 0, v[0:1]
	v_add_co_u32_e32 v4, vcc, 0x1000, v4
	v_add_u32_e32 v3, s10, v7
	s_nop 0
	v_addc_co_u32_e32 v5, vcc, 0, v5, vcc
	global_load_dword v240, v[4:5], off offset:3904
	v_or_b32_e32 v0, 0x200, v7
	v_lshl_add_u64 v[4:5], s[94:95], 0, v[0:1]
	v_add_co_u32_e32 v4, vcc, 0x1000, v4
	s_nop 1
	v_addc_co_u32_e32 v5, vcc, 0, v5, vcc
	global_load_dword v241, v[4:5], off offset:3904
	global_load_dword v0, v1, s[86:87]
	v_sub_u32_e32 v4, 64, v209
	v_lshrrev_b32_e32 v4, 6, v4
	v_cmp_ne_u32_e32 vcc, 0, v4
	s_waitcnt vmcnt(0)
	ds_write2st64_b32 v3, v6, v240 offset0:48 offset1:49
	ds_write_b32 v3, v241 offset:12800
	s_mov_b64 s[34:35], exec
	s_mov_b64 s[40:41], -1
	s_and_b64 s[40:41], s[34:35], s[40:41]
	s_mov_b64 exec, s[40:41]
	s_cbranch_execz .LBB0_465
	s_waitcnt vmcnt(0)
	ds_write_b32 v3, v0 offset:13056
